# v64 + dead waits and self-copies removed from the P7 last-iteration path (.LBB0_651/.LBB0_673)
# baseline (speedup 1.0000x reference)
; template <int DIR>
; __device__ __forceinline__ void s5_local_dir(const bf16_t* UZ, unsigned char* ws, int gw, int NGW, int lane) {
;     ...
;     for (int c = c0; c < c1; ++c) {
;         bf16x4 Uf[4];
; #pragma unroll
;         for (int m = 0; m < 4; ++m) Uf[m] = Un[m];
;         if (c + 1 < c1) load_uf(Un, UZ, chunk_rowbase(b, DIR, c + 1), g, lane);
;         float* e = ebase + (size_t)c * 128;
; #pragma unroll
;         for (int t = 0; t < 4; ++t) {
;             f32x4 cr = {0.f, 0.f, 0.f, 0.f}, ci = {0.f, 0.f, 0.f, 0.f};
; #pragma unroll
;             for (int m = 0; m < 4; ++m) {
;                 cr = __builtin_amdgcn_mfma_f32_16x16x16bf16_1k(Uf[m], Bre[m][t], cr, 0, 0, 0);
;                 ci = __builtin_amdgcn_mfma_f32_16x16x16bf16_1k(Uf[m], Bim[m][t], ci, 0, 0, 0);
;             }
;             f32x2 s2 = {DIR ? cr[3] : cr[0], DIR ? ci[3] : ci[0]};
; #pragma unroll
;             for (int ii = 1; ii < 4; ++ii) { const int i = DIR ? 3 - ii : ii;
;                 s2 = cmac(s2, (f32x2){a1r[t], a1r[t]}, (f32x2){-a1i[t], a1i[t]}, (f32x2){cr[i], ci[i]}); }
;             s2 = cmac(s2, (f32x2){wr_[t], wr_[t]}, (f32x2){-wi_[t], wi_[t]}, (f32x2){0.f, 0.f});
;             float sr = s2.x, si = s2.y;
;             sr += __shfl_xor(sr, 16); si += __shfl_xor(si, 16); sr += __shfl_xor(sr, 32); si += __shfl_xor(si, 32);
;             if (fq == 0) { e[16 * t + fr] = Rr[t]; e[64 + 16 * t + fr] = Ri[t]; }
;             const float nr = fmaf(a64r[t], Rr[t], fmaf(-a64i[t], Ri[t], sr)), ni = fmaf(a64r[t], Ri[t], fmaf(a64i[t], Rr[t], si)); Rr[t] = nr; Ri[t] = ni;
;         }
.LBB0_651:
.LBB0_652:
	global_store_dword v[116:117], v240, off offset:-256
	global_store_dword v[116:117], v241, off
	s_waitcnt vmcnt(9)
	v_mfma_f32_16x16x32_bf16 v[140:143], v[108:111], v[26:29], 0
	v_mfma_f32_16x16x32_bf16 v[144:147], v[108:111], v[34:37], 0
	v_mfma_f32_16x16x32_bf16 v[196:199], v[108:111], v[48:51], 0
	v_mfma_f32_16x16x32_bf16 v[200:203], v[108:111], v[56:59], 0
	v_mfma_f32_16x16x32_bf16 v[208:211], v[108:111], v[70:73], 0
	v_mfma_f32_16x16x32_bf16 v[212:215], v[108:111], v[78:81], 0
	v_mfma_f32_16x16x32_bf16 v[228:231], v[108:111], v[92:95], 0
	v_mfma_f32_16x16x32_bf16 v[184:187], v[108:111], v[100:103], 0
	v_mfma_f32_16x16x32_bf16 v[140:143], v[112:115], v[30:33], v[140:143]
	v_mfma_f32_16x16x32_bf16 v[144:147], v[112:115], v[38:41], v[144:147]
	v_mfma_f32_16x16x32_bf16 v[196:199], v[112:115], v[52:55], v[196:199]
	v_mfma_f32_16x16x32_bf16 v[200:203], v[112:115], v[60:63], v[200:203]
	v_mfma_f32_16x16x32_bf16 v[208:211], v[112:115], v[74:77], v[208:211]
	v_mfma_f32_16x16x32_bf16 v[212:215], v[112:115], v[82:85], v[212:215]
	v_mfma_f32_16x16x32_bf16 v[228:231], v[112:115], v[96:99], v[228:231]
	v_mfma_f32_16x16x32_bf16 v[184:187], v[112:115], v[104:107], v[184:187]
	s_nop 6
	v_mov_b32_e32 v148, v143
	v_mov_b32_e32 v204, v199
	v_mov_b32_e32 v216, v211
	v_mov_b32_e32 v190, v231
	v_mov_b32_e32 v149, v147
	v_mov_b32_e32 v205, v203
	v_mov_b32_e32 v217, v215
	v_mov_b32_e32 v191, v187
	v_mov_b32_e32 v150, v142
	v_mov_b32_e32 v206, v198
	v_mov_b32_e32 v218, v210
	v_mov_b32_e32 v188, v230
	v_mov_b32_e32 v151, v146
	v_mov_b32_e32 v207, v202
	v_mov_b32_e32 v219, v214
	v_mov_b32_e32 v189, v186
	v_pk_fma_f32 v[148:149], v[20:21], v[148:149], v[150:151]
	v_pk_fma_f32 v[204:205], v[42:43], v[204:205], v[206:207]
	v_pk_fma_f32 v[216:217], v[64:65], v[216:217], v[218:219]
	v_pk_fma_f32 v[188:189], v[86:87], v[190:191], v[188:189]
	v_mov_b32_e32 v142, v147
	v_mov_b32_e32 v198, v203
	v_mov_b32_e32 v210, v215
	v_mov_b32_e32 v230, v187
	v_pk_fma_f32 v[142:143], v[0:1], v[142:143], v[148:149]
	v_pk_fma_f32 v[198:199], v[4:5], v[198:199], v[204:205]
	v_pk_fma_f32 v[210:211], v[8:9], v[210:211], v[216:217]
	v_pk_fma_f32 v[186:187], v[12:13], v[230:231], v[188:189]
	v_mov_b32_e32 v146, v141
	v_mov_b32_e32 v202, v197
	v_mov_b32_e32 v214, v209
	v_mov_b32_e32 v188, v229
	v_mov_b32_e32 v147, v145
	v_mov_b32_e32 v203, v201
	v_mov_b32_e32 v215, v213
	v_mov_b32_e32 v189, v185
	v_pk_fma_f32 v[146:147], v[20:21], v[142:143], v[146:147]
	v_pk_fma_f32 v[202:203], v[42:43], v[198:199], v[202:203]
	v_pk_fma_f32 v[214:215], v[64:65], v[210:211], v[214:215]
	v_pk_fma_f32 v[188:189], v[86:87], v[186:187], v[188:189]
	v_mov_b32_e32 v141, v144
	v_mov_b32_e32 v197, v200
	v_mov_b32_e32 v209, v212
	v_mov_b32_e32 v229, v184
	v_pk_fma_f32 v[142:143], v[0:1], v[142:143], v[146:147] op_sel:[0,1,0] op_sel_hi:[1,0,1]
	v_pk_fma_f32 v[198:199], v[4:5], v[198:199], v[202:203] op_sel:[0,1,0] op_sel_hi:[1,0,1]
	v_pk_fma_f32 v[210:211], v[8:9], v[210:211], v[214:215] op_sel:[0,1,0] op_sel_hi:[1,0,1]
	v_pk_fma_f32 v[186:187], v[12:13], v[186:187], v[188:189] op_sel:[0,1,0] op_sel_hi:[1,0,1]
	s_nop 0
	s_nop 0
	s_nop 0
	s_nop 0
	v_pk_fma_f32 v[140:141], v[20:21], v[142:143], v[140:141]
	v_pk_fma_f32 v[196:197], v[42:43], v[198:199], v[196:197]
	v_pk_fma_f32 v[208:209], v[64:65], v[210:211], v[208:209]
	v_pk_fma_f32 v[184:185], v[86:87], v[186:187], v[228:229]
	s_nop 0
	s_nop 0
	s_nop 0
	s_nop 0
	v_pk_fma_f32 v[140:141], v[0:1], v[142:143], v[140:141] op_sel:[0,1,0] op_sel_hi:[1,0,1]
	v_pk_fma_f32 v[196:197], v[4:5], v[198:199], v[196:197] op_sel:[0,1,0] op_sel_hi:[1,0,1]
	v_pk_fma_f32 v[208:209], v[8:9], v[210:211], v[208:209] op_sel:[0,1,0] op_sel_hi:[1,0,1]
	v_pk_fma_f32 v[184:185], v[12:13], v[186:187], v[184:185] op_sel:[0,1,0] op_sel_hi:[1,0,1]
	s_nop 0
	s_nop 0
	s_nop 0
	s_nop 0
	v_pk_fma_f32 v[142:143], v[22:23], v[140:141], 0 op_sel_hi:[1,1,0]
	v_pk_fma_f32 v[198:199], v[44:45], v[196:197], 0 op_sel_hi:[1,1,0]
	v_pk_fma_f32 v[210:211], v[66:67], v[208:209], 0 op_sel_hi:[1,1,0]
	v_pk_fma_f32 v[186:187], v[88:89], v[184:185], 0 op_sel_hi:[1,1,0]
	s_nop 0
	s_nop 0
	s_nop 0
	s_nop 0
	v_pk_fma_f32 v[140:141], v[24:25], v[140:141], v[142:143] op_sel:[0,1,0] op_sel_hi:[1,0,1]
	v_pk_fma_f32 v[196:197], v[46:47], v[196:197], v[198:199] op_sel:[0,1,0] op_sel_hi:[1,0,1]
	v_pk_fma_f32 v[208:209], v[68:69], v[208:209], v[210:211] op_sel:[0,1,0] op_sel_hi:[1,0,1]
	v_pk_fma_f32 v[184:185], v[90:91], v[184:185], v[186:187] op_sel:[0,1,0] op_sel_hi:[1,0,1]
	s_nop 1
	v_permlane32_swap_b32_e32 v140, v208
	v_permlane32_swap_b32_e32 v141, v209
	v_permlane32_swap_b32_e32 v196, v184
	v_permlane32_swap_b32_e32 v197, v185
	v_add_f32_e32 v140, v140, v208
	v_add_f32_e32 v196, v196, v184
	v_add_f32_e32 v141, v141, v209
	v_add_f32_e32 v197, v197, v185
	s_nop 0
	v_permlane16_swap_b32_e32 v140, v196
	v_permlane16_swap_b32_e32 v141, v197
	v_add_f32_e32 v140, v140, v196
	v_add_f32_e32 v141, v141, v197
	v_fma_f32 v244, -v243, v241, v140
	v_fma_f32 v245, v243, v240, v141
	v_fma_f32 v240, v242, v240, v244
	v_fma_f32 v241, v242, v241, v245
	v_lshl_add_u64 v[116:117], v[116:117], 0, s[2:3]
	v_subrev_u32_e32 v16, 64, v16
	s_and_b64 vcc, exec, s[36:37]
	s_cbranch_vccnz .LBB0_684
	s_mov_b32 s38, s49
	s_waitcnt vmcnt(3)
	v_mov_b32_e32 v110, v118
	v_mov_b32_e32 v111, v119
	s_waitcnt vmcnt(2)
	v_mov_b32_e32 v112, v120
	v_mov_b32_e32 v113, v121
	s_waitcnt vmcnt(1)
	v_mov_b32_e32 v114, v122
	v_mov_b32_e32 v115, v123
	s_waitcnt vmcnt(0)
	v_mov_b32_e32 v108, v124
	v_mov_b32_e32 v109, v125
	s_branch .LBB0_649

; template <int DIR>
; __device__ __forceinline__ void s5_local_dir(const bf16_t* UZ, unsigned char* ws, int gw, int NGW, int lane) {
;     ...
;     for (int c = c0; c < c1; ++c) {
;         bf16x4 Uf[4];
; #pragma unroll
;         for (int m = 0; m < 4; ++m) Uf[m] = Un[m];
;         if (c + 1 < c1) load_uf(Un, UZ, chunk_rowbase(b, DIR, c + 1), g, lane);
;         float* e = ebase + (size_t)c * 128;
; #pragma unroll
;         for (int t = 0; t < 4; ++t) {
;             f32x4 cr = {0.f, 0.f, 0.f, 0.f}, ci = {0.f, 0.f, 0.f, 0.f};
; #pragma unroll
;             for (int m = 0; m < 4; ++m) {
;                 cr = __builtin_amdgcn_mfma_f32_16x16x16bf16_1k(Uf[m], Bre[m][t], cr, 0, 0, 0);
;                 ci = __builtin_amdgcn_mfma_f32_16x16x16bf16_1k(Uf[m], Bim[m][t], ci, 0, 0, 0);
;             }
;             f32x2 s2 = {DIR ? cr[3] : cr[0], DIR ? ci[3] : ci[0]};
; #pragma unroll
;             for (int ii = 1; ii < 4; ++ii) { const int i = DIR ? 3 - ii : ii;
;                 s2 = cmac(s2, (f32x2){a1r[t], a1r[t]}, (f32x2){-a1i[t], a1i[t]}, (f32x2){cr[i], ci[i]}); }
;             s2 = cmac(s2, (f32x2){wr_[t], wr_[t]}, (f32x2){-wi_[t], wi_[t]}, (f32x2){0.f, 0.f});
;             float sr = s2.x, si = s2.y;
;             sr += __shfl_xor(sr, 16); si += __shfl_xor(si, 16); sr += __shfl_xor(sr, 32); si += __shfl_xor(si, 32);
;             if (fq == 0) { e[16 * t + fr] = Rr[t]; e[64 + 16 * t + fr] = Ri[t]; }
;             const float nr = fmaf(a64r[t], Rr[t], fmaf(-a64i[t], Ri[t], sr)), ni = fmaf(a64r[t], Ri[t], fmaf(a64i[t], Rr[t], si)); Rr[t] = nr; Ri[t] = ni;
;         }
.LBB0_673:
.LBB0_674:
	global_store_dword v[116:117], v240, off offset:-256
	global_store_dword v[116:117], v241, off
	s_waitcnt vmcnt(9)
	v_mfma_f32_16x16x32_bf16 v[136:139], v[108:111], v[26:29], 0
	v_mfma_f32_16x16x32_bf16 v[140:143], v[108:111], v[34:37], 0
	v_mfma_f32_16x16x32_bf16 v[196:199], v[108:111], v[48:51], 0
	v_mfma_f32_16x16x32_bf16 v[200:203], v[108:111], v[56:59], 0
	v_mfma_f32_16x16x32_bf16 v[208:211], v[108:111], v[70:73], 0
	v_mfma_f32_16x16x32_bf16 v[212:215], v[108:111], v[78:81], 0
	v_mfma_f32_16x16x32_bf16 v[224:227], v[108:111], v[88:91], 0
	v_mfma_f32_16x16x32_bf16 v[184:187], v[108:111], v[100:103], 0
	v_mfma_f32_16x16x32_bf16 v[136:139], v[112:115], v[30:33], v[136:139]
	v_mfma_f32_16x16x32_bf16 v[140:143], v[112:115], v[38:41], v[140:143]
	v_mfma_f32_16x16x32_bf16 v[196:199], v[112:115], v[52:55], v[196:199]
	v_mfma_f32_16x16x32_bf16 v[200:203], v[112:115], v[60:63], v[200:203]
	v_mfma_f32_16x16x32_bf16 v[208:211], v[112:115], v[74:77], v[208:211]
	v_mfma_f32_16x16x32_bf16 v[212:215], v[112:115], v[82:85], v[212:215]
	v_mfma_f32_16x16x32_bf16 v[224:227], v[112:115], v[96:99], v[224:227]
	v_mfma_f32_16x16x32_bf16 v[184:187], v[112:115], v[104:107], v[184:187]
	s_nop 6
	v_mov_b32_e32 v144, v136
	v_mov_b32_e32 v204, v196
	v_mov_b32_e32 v216, v208
	v_mov_b32_e32 v228, v224
	v_mov_b32_e32 v145, v140
	v_mov_b32_e32 v205, v200
	v_mov_b32_e32 v217, v212
	v_mov_b32_e32 v229, v184
	v_mov_b32_e32 v146, v137
	v_mov_b32_e32 v206, v197
	v_mov_b32_e32 v218, v209
	v_mov_b32_e32 v188, v225
	v_mov_b32_e32 v147, v141
	v_mov_b32_e32 v207, v201
	v_mov_b32_e32 v219, v213
	v_mov_b32_e32 v189, v185
	v_pk_fma_f32 v[144:145], v[18:19], v[144:145], v[146:147]
	v_pk_fma_f32 v[204:205], v[42:43], v[204:205], v[206:207]
	v_pk_fma_f32 v[216:217], v[64:65], v[216:217], v[218:219]
	v_pk_fma_f32 v[188:189], v[86:87], v[228:229], v[188:189]
	v_mov_b32_e32 v141, v136
	v_mov_b32_e32 v201, v196
	v_mov_b32_e32 v213, v208
	v_mov_b32_e32 v185, v224
	v_pk_fma_f32 v[136:137], v[0:1], v[140:141], v[144:145]
	v_pk_fma_f32 v[196:197], v[4:5], v[200:201], v[204:205]
	v_pk_fma_f32 v[208:209], v[8:9], v[212:213], v[216:217]
	v_pk_fma_f32 v[184:185], v[12:13], v[184:185], v[188:189]
	v_mov_b32_e32 v140, v138
	v_mov_b32_e32 v200, v198
	v_mov_b32_e32 v212, v210
	v_mov_b32_e32 v188, v226
	v_mov_b32_e32 v141, v142
	v_mov_b32_e32 v201, v202
	v_mov_b32_e32 v213, v214
	v_mov_b32_e32 v189, v186
	v_pk_fma_f32 v[140:141], v[18:19], v[136:137], v[140:141]
	v_pk_fma_f32 v[200:201], v[42:43], v[196:197], v[200:201]
	v_pk_fma_f32 v[212:213], v[64:65], v[208:209], v[212:213]
	v_pk_fma_f32 v[188:189], v[86:87], v[184:185], v[188:189]
	v_mov_b32_e32 v142, v139
	v_mov_b32_e32 v202, v199
	v_mov_b32_e32 v214, v211
	v_mov_b32_e32 v186, v227
	v_pk_fma_f32 v[136:137], v[0:1], v[136:137], v[140:141] op_sel:[0,1,0] op_sel_hi:[1,0,1]
	v_pk_fma_f32 v[196:197], v[4:5], v[196:197], v[200:201] op_sel:[0,1,0] op_sel_hi:[1,0,1]
	v_pk_fma_f32 v[208:209], v[8:9], v[208:209], v[212:213] op_sel:[0,1,0] op_sel_hi:[1,0,1]
	v_pk_fma_f32 v[184:185], v[12:13], v[184:185], v[188:189] op_sel:[0,1,0] op_sel_hi:[1,0,1]
	s_nop 0
	s_nop 0
	s_nop 0
	s_nop 0
	v_pk_fma_f32 v[138:139], v[18:19], v[136:137], v[142:143]
	v_pk_fma_f32 v[198:199], v[42:43], v[196:197], v[202:203]
	v_pk_fma_f32 v[210:211], v[64:65], v[208:209], v[214:215]
	v_pk_fma_f32 v[186:187], v[86:87], v[184:185], v[186:187]
	s_nop 0
	s_nop 0
	s_nop 0
	s_nop 0
	v_pk_fma_f32 v[136:137], v[0:1], v[136:137], v[138:139] op_sel:[0,1,0] op_sel_hi:[1,0,1]
	v_pk_fma_f32 v[196:197], v[4:5], v[196:197], v[198:199] op_sel:[0,1,0] op_sel_hi:[1,0,1]
	v_pk_fma_f32 v[208:209], v[8:9], v[208:209], v[210:211] op_sel:[0,1,0] op_sel_hi:[1,0,1]
	v_pk_fma_f32 v[184:185], v[12:13], v[184:185], v[186:187] op_sel:[0,1,0] op_sel_hi:[1,0,1]
	s_nop 0
	s_nop 0
	s_nop 0
	s_nop 0
	v_pk_fma_f32 v[138:139], v[22:23], v[136:137], 0 op_sel_hi:[1,1,0]
	v_pk_fma_f32 v[198:199], v[44:45], v[196:197], 0 op_sel_hi:[1,1,0]
	v_pk_fma_f32 v[210:211], v[66:67], v[208:209], 0 op_sel_hi:[1,1,0]
	v_pk_fma_f32 v[186:187], v[92:93], v[184:185], 0 op_sel_hi:[1,1,0]
	s_nop 0
	s_nop 0
	s_nop 0
	s_nop 0
	v_pk_fma_f32 v[136:137], v[24:25], v[136:137], v[138:139] op_sel:[0,1,0] op_sel_hi:[1,0,1]
	v_pk_fma_f32 v[196:197], v[46:47], v[196:197], v[198:199] op_sel:[0,1,0] op_sel_hi:[1,0,1]
	v_pk_fma_f32 v[208:209], v[68:69], v[208:209], v[210:211] op_sel:[0,1,0] op_sel_hi:[1,0,1]
	v_pk_fma_f32 v[184:185], v[94:95], v[184:185], v[186:187] op_sel:[0,1,0] op_sel_hi:[1,0,1]
	s_nop 1
	v_permlane32_swap_b32_e32 v136, v208
	v_permlane32_swap_b32_e32 v137, v209
	v_permlane32_swap_b32_e32 v196, v184
	v_permlane32_swap_b32_e32 v197, v185
	v_add_f32_e32 v136, v136, v208
	v_add_f32_e32 v196, v196, v184
	v_add_f32_e32 v137, v137, v209
	v_add_f32_e32 v197, v197, v185
	s_nop 0
	v_permlane16_swap_b32_e32 v136, v196
	v_permlane16_swap_b32_e32 v137, v197
	v_add_f32_e32 v136, v136, v196
	v_add_f32_e32 v137, v137, v197
	v_fma_f32 v244, -v243, v241, v136
	v_fma_f32 v245, v243, v240, v137
	v_fma_f32 v240, v242, v240, v244
	v_fma_f32 v241, v242, v241, v245
	v_lshl_add_u64 v[116:117], v[116:117], 0, s[4:5]
	v_add_u32_e32 v20, 64, v20
	s_and_b64 vcc, exec, s[22:23]
	s_cbranch_vccnz .LBB0_702
	s_mov_b32 s24, s40
	s_waitcnt vmcnt(3)
	v_mov_b32_e32 v108, v118
	v_mov_b32_e32 v109, v119
	s_waitcnt vmcnt(2)
	v_mov_b32_e32 v112, v120
	v_mov_b32_e32 v113, v121
	s_waitcnt vmcnt(1)
	v_mov_b32_e32 v114, v122
	v_mov_b32_e32 v115, v123
	s_waitcnt vmcnt(0)
	v_mov_b32_e32 v110, v124
	v_mov_b32_e32 v111, v125
	s_branch .LBB0_671
